# P5 up-proj: 6 full rounds + the 48 leftover tiles run by 48 workgroups idle in P6, concurrently with P6 (they then do the P6 tasks/copies that depend on their tile); decode rows of xb copied aside bec
# baseline (speedup 1.0000x reference)
.LBB0_936:
	s_or_b64 exec, exec, s[4:5]
	s_mov_b32 s101, 0
.Lt5_entry:
	s_cmp_lg_u32 s101, 0
	s_cbranch_scc1 .Lt5_nocp
	s_lshl_b32 s4, s2, 9
	v_add_lshl_u32 v0, s4, v176, 5
	s_add_u32 s4, s30, 0x10a00000
	s_addc_u32 s5, s31, 0
	global_load_dwordx4 v[2:5], v0, s[4:5]
	global_load_dwordx4 v[6:9], v0, s[4:5] offset:16
	s_add_u32 s4, s30, 0xc600000
	s_addc_u32 s5, s31, 0
	s_waitcnt vmcnt(0)
	global_store_dwordx4 v0, v[2:5], s[4:5]
	global_store_dwordx4 v0, v[6:9], s[4:5] offset:16
.Lt5_nocp:
	v_mov_b32_e32 v14, v176
	s_waitcnt lgkmcnt(0)
	s_barrier
	s_cmpk_gt_i32 s2, 0x62f
	s_nop 0
	v_readfirstlane_b32 s24, v14
	s_cbranch_scc1 .LBB0_948
	v_lshlrev_b32_e32 v0, 4, v14
	v_add_u32_e32 v1, 0x2000, v0
	v_ashrrev_i32_e32 v2, 31, v1
	v_lshrrev_b32_e32 v2, 22, v2
	v_add_u32_e32 v2, v1, v2
	v_ashrrev_i32_e32 v8, 10, v2
	v_mul_i32_i24_e32 v2, 0x400, v8
	v_sub_u32_e32 v1, v1, v2
	v_lshrrev_b32_e32 v2, 4, v1
	v_bitop3_b32 v1, v2, v1, 32 bitop3:0x6c
	v_ashrrev_i32_e32 v2, 31, v1
	v_lshrrev_b32_e32 v2, 26, v2
	v_add_u32_e32 v2, v1, v2
	v_lshlrev_b32_e32 v3, 3, v8
	v_ashrrev_i32_e32 v9, 6, v2
	v_and_b32_e32 v3, -16, v3
	v_add_u32_e32 v3, v9, v3
	v_and_b32_e32 v4, 3, v9
	s_mov_b32 s4, 0xfffe0
	v_lshrrev_b32_e32 v5, 2, v3
	v_lshlrev_b32_e32 v6, 1, v3
	v_and_b32_e32 v2, 0xc0, v2
	v_and_or_b32 v4, v3, s4, v4
	v_and_b32_e32 v5, 4, v5
	v_and_b32_e32 v6, 24, v6
	v_sub_u32_e32 v1, v1, v2
	v_mov_b32_e32 v2, 1
	v_or3_b32 v4, v4, v5, v6
	v_lshlrev_b32_e32 v5, 5, v8
	v_ashrrev_i16_sdwa v1, v2, sext(v1) dst_sel:DWORD dst_unused:UNUSED_PAD src0_sel:DWORD src1_sel:BYTE_0
	v_and_b32_e32 v5, 32, v5
	v_bfe_i32 v10, v1, 0, 16
	v_add_lshl_u32 v1, v5, v10, 1
	v_lshl_add_u32 v128, v4, 12, v1
	v_lshl_add_u32 v130, v3, 12, v1
	v_bfe_i32 v1, v14, 27, 1
	v_lshrrev_b32_e32 v1, 22, v1
	v_add_u32_e32 v1, v0, v1
	v_and_b32_e32 v1, 0xfffffc00, v1
	v_sub_u32_e32 v0, v0, v1
	v_lshrrev_b32_e32 v1, 4, v0
	v_bitop3_b32 v1, v1, v0, 32 bitop3:0x6c
	v_ashrrev_i32_e32 v0, 31, v0
	v_lshrrev_b32_e32 v0, 26, v0
	v_add_u32_e32 v0, v1, v0
	v_ashrrev_i32_e32 v11, 6, v0
	v_ashrrev_i32_e32 v0, 31, v14
	v_lshrrev_b32_e32 v0, 26, v0
	v_add_u32_e32 v0, v14, v0
	v_ashrrev_i32_e32 v12, 6, v0
	v_lshlrev_b32_e32 v0, 3, v12
	v_and_b32_e32 v0, -16, v0
	v_add_u32_e32 v0, v11, v0
	v_and_b32_e32 v3, 3, v11
	v_and_or_b32 v3, v0, s4, v3
	s_lshr_b32 s4, s3, 29
	s_add_i32 s4, s2, s4
	s_ashr_i32 s5, s24, 6
	s_ashr_i32 s7, s4, 3
	s_and_b32 s4, s4, -8
	s_ashr_i32 s6, s24, 8
	s_lshl_b32 s25, s5, 10
	s_sub_i32 s4, s2, s4
	s_cmp_lt_i32 s4, 0
	s_movk_i32 s26, 0xc7
	s_cselect_b32 s10, s26, 0xc0
	s_mul_i32 s4, s4, s10
	v_lshrrev_b32_e32 v4, 2, v0
	v_lshlrev_b32_e32 v5, 1, v0
	s_add_i32 s4, s4, s7
	v_and_b32_e32 v4, 4, v4
	v_and_b32_e32 v5, 24, v5
	s_mul_hi_i32 s7, s4, 0x2e8ba2e9
	v_or3_b32 v3, v3, v4, v5
	v_mul_i32_i24_e32 v5, 64, v11
	s_lshr_b32 s10, s7, 31
	s_ashr_i32 s7, s7, 6
	v_sub_u32_e32 v1, v1, v5
	s_add_i32 s7, s7, s10
	v_lshlrev_b32_e32 v4, 5, v12
	v_ashrrev_i16_sdwa v1, v2, sext(v1) dst_sel:DWORD dst_unused:UNUSED_PAD src0_sel:DWORD src1_sel:BYTE_0
	s_lshl_b32 s12, s7, 3
	v_and_b32_e32 v4, 32, v4
	v_bfe_i32 v13, v1, 0, 16
	s_sub_i32 s10, 36, s12
	s_mulk_i32 s7, 0x160
	v_add_lshl_u32 v1, v4, v13, 1
	s_min_u32 s13, s10, 8
	s_sub_i32 s7, s4, s7
	v_lshl_add_u32 v132, v3, 12, v1
	s_sext_i32_i16 s4, s7
	v_cvt_f32_ubyte0_e32 v3, s13
	v_cvt_f32_i32_e32 v2, s4
	v_rcp_iflag_f32_e32 v4, v3
	v_lshl_add_u32 v134, v0, 12, v1
	s_ashr_i32 s4, s4, 30
	s_or_b32 s4, s4, 1
	v_mul_f32_e32 v0, v2, v4
	v_trunc_f32_e32 v0, v0
	v_fma_f32 v1, -v0, v3, v2
	v_cvt_i32_f32_e32 v0, v0
	v_cmp_ge_f32_e64 s[10:11], |v1|, v3
	s_and_b64 s[10:11], s[10:11], exec
	s_cselect_b32 s4, s4, 0
	v_readfirstlane_b32 s10, v0
	s_add_i32 s4, s10, s4
	s_mul_i32 s10, s4, s13
	s_sub_i32 s7, s7, s10
	s_sext_i32_i16 s7, s7
	s_add_i32 s16, s12, s7
	s_cmp_eq_u32 s101, 0
	s_cbranch_scc1 .Lt5_sel
	s_sub_i32 s7, s2, 0xd0
	s_and_b32 s16, s7, 3
	s_add_i32 s16, s16, 32
	s_lshr_b32 s4, s7, 2
	s_add_i32 s4, s4, 32
.Lt5_sel:
	s_ashr_i32 s17, s16, 31
	s_bfe_i64 s[12:13], s[4:5], 0x100000
	s_lshl_b64 s[10:11], s[16:17], 20
	s_lshl_b64 s[12:13], s[12:13], 20
	v_readlane_b32 s14, v239, 7
	v_readlane_b32 s15, v239, 8
	s_add_u32 s20, s14, s12
	s_addc_u32 s21, s15, s13
	s_add_i32 s17, s25, 0
	s_add_i32 m0, s17, 0x10000
	v_mov_b32_e32 v133, 0
	global_load_lds_dwordx4 v132, s[20:21]
	s_add_i32 m0, s17, 0x12000
	s_add_u32 s18, s0, s10
	global_load_lds_dwordx4 v128, s[20:21]
	s_addc_u32 s19, s1, s11
	s_mov_b32 m0, s17
	s_add_i32 s27, s17, 0x2000
	global_load_lds_dwordx4 v134, s[18:19]
	s_mov_b32 m0, s27
	s_add_u32 s10, s20, 0x80000
	global_load_lds_dwordx4 v130, s[18:19]
	s_addc_u32 s11, s21, 0
	s_add_i32 m0, s17, 0x14000
	v_mov_b32_e32 v129, v133
	global_load_lds_dwordx4 v132, s[10:11]
	s_add_i32 m0, s17, 0x16000
	v_mov_b32_e32 v135, v133
	global_load_lds_dwordx4 v128, s[10:11]
	s_add_u32 s10, s18, 0x80000
	s_addc_u32 s11, s19, 0
	s_add_i32 s33, s17, 0x4000
	s_mov_b32 m0, s33
	s_add_i32 s35, s17, 0x6000
	global_load_lds_dwordx4 v134, s[10:11]
	s_mov_b32 m0, s35
	v_mov_b32_e32 v131, v133
	global_load_lds_dwordx4 v130, s[10:11]
	s_lshl_b32 s36, s101, 8
	v_lshl_add_u64 v[6:7], s[20:21], 0, v[132:133]
	v_lshl_add_u64 v[4:5], s[20:21], 0, v[128:129]
	v_lshl_add_u64 v[2:3], s[18:19], 0, v[134:135]
	s_cmp_lg_u32 s6, 1
	v_lshl_add_u64 v[0:1], s[18:19], 0, v[130:131]
	s_cbranch_scc1 .LBB0_939
	s_barrier
.LBB0_939:
	v_bfe_u32 v16, v14, 4, 2
	v_and_b32_e32 v15, 15, v14
	v_lshlrev_b32_e32 v17, 4, v16
	v_lshlrev_b32_e32 v14, 2, v14
	s_sext_i32_i16 s43, s4
	v_lshl_or_b32 v152, s6, 6, v15
	v_lshl_or_b32 v15, v15, 6, v17
	s_lshl_b32 s4, s6, 13
	v_and_b32_e32 v14, 32, v14
	v_bitop3_b32 v17, v15, s4, v14 bitop3:0xde
	s_lshl_b32 s4, s5, 5
	s_mov_b64 s[6:7], 0x80
	s_and_b32 s10, s4, 0x60
	s_add_i32 m0, s17, 0x18000
	v_lshl_add_u64 v[6:7], v[6:7], 0, s[6:7]
	s_lshl_b32 s4, s10, 7
	s_waitcnt vmcnt(4)
	s_barrier
	global_load_lds_dwordx4 v[6:7], off
	v_lshl_add_u64 v[4:5], v[4:5], 0, s[6:7]
	s_add_i32 m0, s17, 0x1a000
	s_add_i32 s37, s17, 0x8000
	s_add_i32 s38, s17, 0xa000
	v_bitop3_b32 v153, v15, s4, v14 bitop3:0xde
	global_load_lds_dwordx4 v[4:5], off
	v_lshl_add_u64 v[2:3], v[2:3], 0, s[6:7]
	s_mov_b32 m0, s37
	s_add_u32 s4, s20, 0x80080
	global_load_lds_dwordx4 v[2:3], off
	v_lshl_add_u64 v[0:1], v[0:1], 0, s[6:7]
	s_mov_b32 m0, s38
	s_addc_u32 s5, s21, 0
	global_load_lds_dwordx4 v[0:1], off
	s_add_i32 m0, s17, 0x1c000
	v_lshl_add_u64 v[0:1], s[4:5], 0, v[132:133]
	global_load_lds_dwordx4 v[0:1], off
	v_lshl_add_u64 v[0:1], s[4:5], 0, v[128:129]
	s_add_i32 m0, s17, 0x1e000
	s_add_i32 s39, 0, 0x10000
	global_load_lds_dwordx4 v[0:1], off
	v_lshlrev_b32_e32 v0, 5, v16
	v_mov_b32_e32 v1, v133
	v_lshl_add_u64 v[136:137], s[8:9], 0, v[0:1]
	v_lshlrev_b32_e32 v0, 15, v12
	v_and_b32_e32 v0, 0xffff0000, v0
	v_lshl_add_u32 v0, v11, 12, v0
	v_and_b32_e32 v1, 1, v12
	v_lshl_or_b32 v0, v1, 6, v0
	v_lshl_add_u32 v138, v13, 1, v0
	v_lshlrev_b32_e32 v0, 15, v8
	v_and_b32_e32 v0, 0xffff0000, v0
	v_lshl_add_u32 v0, v9, 12, v0
	v_and_b32_e32 v1, 1, v8
	s_waitcnt vmcnt(6)
	v_lshl_or_b32 v0, v1, 6, v0
	v_lshl_add_u32 v140, v10, 1, v0
	s_add_i32 s40, 0, 0x14000
	v_mbcnt_lo_u32_b32 v0, -1, 0
	v_lshl_or_b32 v154, v16, 3, s10
	v_mov_b32_e32 v139, v133
	v_mov_b32_e32 v141, v133
	v_mov_b64_e32 v[142:143], 0x600
	v_mov_b64_e32 v[144:145], 0x5ff
	v_add_u32_e32 v155, s39, v153
	v_add_u32_e32 v156, 0, v17
	v_add_u32_e32 v157, s40, v153
	v_mbcnt_hi_u32_b32 v158, -1, v0
	v_mov_b32_e32 v159, 0x358637bd
	s_mov_b32 s41, 0x800000
	s_movk_i32 s42, 0x5800
	s_barrier
.LBB0_940:
	s_add_i32 s36, s36, 1
	v_readlane_b32 s12, v239, 2
	s_mul_i32 s4, s36, s55
	s_mul_hi_u32 s5, s36, s12
	s_add_i32 s5, s5, s4
	s_mul_i32 s4, s36, s12
	v_readlane_b32 s13, v239, 3
	s_add_u32 s12, s4, s2
	s_addc_u32 s13, s5, s3
	v_cmp_gt_i64_e64 s[4:5], s[12:13], v[144:145]
	s_and_b64 vcc, exec, s[4:5]
	s_cbranch_vccnz .LBB0_942
	s_ashr_i32 s8, s12, 31
	s_lshr_b32 s8, s8, 29
	s_add_i32 s8, s12, s8
	s_ashr_i32 s9, s8, 3
	s_and_b32 s8, s8, -8
	s_sub_i32 s8, s12, s8
	s_cmp_lt_i32 s8, 0
	s_cselect_b32 s10, s26, 0xc0
	s_mul_i32 s8, s8, s10
	s_add_i32 s8, s8, s9
	s_mul_hi_i32 s9, s8, 0x2e8ba2e9
	s_lshr_b32 s10, s9, 31
	s_ashr_i32 s9, s9, 6
	s_add_i32 s9, s9, s10
	s_lshl_b32 s10, s9, 3
	s_sub_i32 s11, 36, s10
	s_min_i32 s11, s11, 8
	s_abs_i32 s14, s11
	v_cvt_f32_u32_e32 v0, s14
	s_sub_i32 s22, 0, s14
	s_mulk_i32 s9, 0x160
	s_sub_i32 s9, s8, s9
	v_rcp_iflag_f32_e32 v0, v0
	s_abs_i32 s8, s9
	s_xor_b32 s15, s9, s11
	s_ashr_i32 s15, s15, 31
	v_mul_f32_e32 v0, 0x4f7ffffe, v0
	v_cvt_u32_f32_e32 v0, v0
	s_nop 0
	v_readfirstlane_b32 s23, v0
	s_mul_i32 s22, s22, s23
	s_mul_hi_u32 s22, s23, s22
	s_add_i32 s23, s23, s22
	s_mul_hi_u32 s22, s8, s23
	s_mul_i32 s23, s22, s14
	s_sub_i32 s8, s8, s23
	s_add_i32 s34, s22, 1
	s_sub_i32 s23, s8, s14
	s_cmp_ge_u32 s8, s14
	s_cselect_b32 s22, s34, s22
	s_cselect_b32 s8, s23, s8
	s_add_i32 s23, s22, 1
	s_cmp_ge_u32 s8, s14
	s_cselect_b32 s8, s23, s22
	s_xor_b32 s8, s8, s15
	s_sub_i32 s8, s8, s15
	s_mul_i32 s11, s8, s11
	s_sub_i32 s9, s9, s11
	s_add_i32 s10, s10, s9

.LBB0_948:
	s_waitcnt vmcnt(0)
	s_barrier
	s_cmp_lg_u32 s101, 0
	s_cbranch_scc1 .Lt5_after
	s_mov_b64 s[0:1], exec
	v_readlane_b32 s4, v239, 4
	v_readlane_b32 s5, v239, 5
	s_and_b64 s[4:5], s[0:1], s[4:5]
	s_mov_b64 exec, s[4:5]
	s_cbranch_execz .LBB0_996
	s_add_i32 s4, 0, 0x21ff0
	v_mov_b32_e32 v0, s4
	s_waitcnt vmcnt(0) expcnt(0) lgkmcnt(0)
	ds_read_b32 v2, v0
	s_add_i32 s4, 0, 0x21ff4
	v_mov_b32_e32 v0, s4
	ds_read_b32 v0, v0
	s_waitcnt lgkmcnt(1)
	v_cmp_ne_u32_e32 vcc, 0, v2
	s_cbranch_vccnz .LBB0_964
	s_mov_b32 s10, 1
	v_mov_b32_e32 v16, 0
	s_branch .LBB0_952

.LBB0_996:
	s_or_b64 exec, exec, s[0:1]
	s_cmp_lt_u32 s2, 0xd0
	s_cbranch_scc1 .Lt5_p6
	s_mov_b32 s101, 1
	s_add_u32 s0, s30, 0xa600000
	s_addc_u32 s1, s31, 0
	s_add_u32 s8, s30, 0x17d29000
	s_addc_u32 s9, s31, 0
	s_branch .Lt5_entry
.Lt5_after:
	s_mov_b32 s101, 2
.Lt5_p6:
	v_readlane_b32 s0, v239, 2
	s_waitcnt lgkmcnt(0)
	v_mov_b32_e32 v0, v176
	s_barrier
	s_lshl_b32 s22, s0, 9
	s_mov_b32 s0, 0x18c00
	v_add_u32_e32 v144, s96, v0
	s_cmp_eq_u32 s101, 2
	s_cbranch_scc1 .Lt5_own
	s_mov_b32 s4, 0x2e8ba2e9
	v_mul_hi_i32 v1, v144, s4
	v_lshrrev_b32_e32 v2, 31, v1
	v_ashrrev_i32_e32 v1, 7, v1
	v_add_u32_e32 v1, v1, v2
	v_mul_i32_i24_e32 v2, 0x2c0, v1
	v_sub_u32_e32 v2, v144, v2
	s_movk_i32 s6, 0x13f
	v_cmp_lt_u32_e32 vcc, 0x7f, v1
	v_cmp_lt_u32_e64 s[4:5], s6, v2
	v_mov_b32_e32 v1, 0x7fffffff
	s_nop 1
	s_and_b64 vcc, vcc, s[4:5]
	s_nop 1
	v_cndmask_b32_e32 v144, v144, v1, vcc
	s_branch .Lt5_tasks
.Lt5_own:
	s_sub_i32 s4, s2, 0xd0
	s_and_b32 s5, s4, 3
	s_lshl_b32 s5, s5, 2
	s_add_i32 s5, s5, 0x80
	s_lshr_b32 s4, s4, 2
	s_lshl_b32 s4, s4, 5
	s_add_i32 s4, s4, 0x140
	s_mul_i32 s5, s5, 0x2c0
	s_add_i32 s4, s4, s5
	v_lshrrev_b32_e32 v1, 5, v0
	v_mul_u32_u24_e32 v1, 0x2c0, v1
	v_and_b32_e32 v2, 31, v0
	v_add3_u32 v144, v1, v2, s4
	v_cmp_gt_u32_e32 vcc, 0x80, v0
	v_mov_b32_e32 v1, 0x7fffffff
	s_nop 1
	v_cndmask_b32_e32 v144, v1, v144, vcc
.Lt5_tasks:
	v_readlane_b32 s1, v239, 3
	v_cmp_gt_i32_e32 vcc, s0, v144
	s_and_saveexec_b64 s[0:1], vcc
	s_cbranch_execz .LBB0_1005
	s_add_u32 s8, s58, 0x5800
	s_addc_u32 s9, s59, 0
	s_add_u32 s10, s56, 0x5800
	s_addc_u32 s11, s57, 0
	s_add_u32 s12, s56, 0xb000
	s_addc_u32 s13, s57, 0
	s_add_u32 s14, s56, 0x10800
	s_addc_u32 s15, s57, 0
	s_add_u32 s16, s56, 0x16000
	s_addc_u32 s17, s57, 0
	s_add_u32 s18, s56, 0x1b800
	s_addc_u32 s19, s57, 0
	s_mov_b64 s[20:21], 0
	s_mov_b32 s23, 0x16000
	s_movk_i32 s24, 0x5800
	s_movk_i32 s25, 0x5000
	s_mov_b32 s26, 0xb000
	s_mov_b32 s27, 0x10000
	v_mov_b32_e32 v145, v144
	s_branch .LBB0_999

.LBB0_1005:
	s_or_b64 exec, exec, s[0:1]
	v_add_u32_e32 v144, s96, v176
	s_cmp_lg_u32 s101, 2
	s_cbranch_scc1 .Lt5_nocopy
	s_mov_b64 s[18:19], exec
	s_sub_i32 s4, s2, 0xd0
	s_and_b32 s5, s4, 3
	s_lshl_b32 s5, s5, 6
	s_lshr_b32 s4, s4, 2
	s_add_i32 s4, s4, 32
	s_lshl_b32 s4, s4, 5
	v_lshrrev_b32_e32 v16, 5, v176
	v_add_u32_e32 v16, s5, v16
	v_mul_u32_u24_e32 v16, 0x580, v16
	v_and_b32_e32 v17, 31, v176
	v_add3_u32 v16, v16, v17, s4
	s_add_i32 s5, s5, 64
	s_mul_i32 s5, s5, 0x580
	s_movk_i32 s16, 0x5800
	s_mov_b32 s4, 0xba2e8ba3
	v_mov_b32_e32 v0, v16
.Lsffn2_loop:
	s_mov_b64 s[6:7], exec
	v_cmp_gt_u32_e64 s[8:9], s5, v0
	v_lshrrev_b32_e32 v12, 7, v0
	v_mul_hi_u32 v12, v12, s4
	v_lshrrev_b32_e32 v12, 3, v12
	v_mul_u32_u24_e32 v13, 0x580, v12
	v_sub_u32_e32 v13, v0, v13
	v_and_b32_e32 v14, 1, v12
	v_sub_u32_e32 v4, v12, v14
	v_lshl_add_u32 v4, v4, 2, v14
	v_add_u32_e32 v4, 0x2006, v4
	v_mul_u32_u24_e32 v4, 0x5800, v4
	v_lshl_add_u32 v4, v13, 4, v4
	v_mul_u32_u24_e32 v8, 0xb000, v12
	v_lshl_add_u32 v8, v13, 5, v8
	v_add_u32_e32 v8, 0xd13e840, v8
	v_add_u32_e32 v1, s16, v0
	v_cmp_gt_u32_e64 s[10:11], s5, v1
	v_lshrrev_b32_e32 v12, 7, v1
	v_mul_hi_u32 v12, v12, s4
	v_lshrrev_b32_e32 v12, 3, v12
	v_mul_u32_u24_e32 v13, 0x580, v12
	v_sub_u32_e32 v13, v1, v13
	v_and_b32_e32 v14, 1, v12
	v_sub_u32_e32 v5, v12, v14
	v_lshl_add_u32 v5, v5, 2, v14
	v_add_u32_e32 v5, 0x2006, v5
	v_mul_u32_u24_e32 v5, 0x5800, v5
	v_lshl_add_u32 v5, v13, 4, v5
	v_mul_u32_u24_e32 v9, 0xb000, v12
	v_lshl_add_u32 v9, v13, 5, v9
	v_add_u32_e32 v9, 0xd13e840, v9
	v_add_u32_e32 v2, s16, v1
	v_cmp_gt_u32_e64 s[12:13], s5, v2
	v_lshrrev_b32_e32 v12, 7, v2
	v_mul_hi_u32 v12, v12, s4
	v_lshrrev_b32_e32 v12, 3, v12
	v_mul_u32_u24_e32 v13, 0x580, v12
	v_sub_u32_e32 v13, v2, v13
	v_and_b32_e32 v14, 1, v12
	v_sub_u32_e32 v6, v12, v14
	v_lshl_add_u32 v6, v6, 2, v14
	v_add_u32_e32 v6, 0x2006, v6
	v_mul_u32_u24_e32 v6, 0x5800, v6
	v_lshl_add_u32 v6, v13, 4, v6
	v_mul_u32_u24_e32 v10, 0xb000, v12
	v_lshl_add_u32 v10, v13, 5, v10
	v_add_u32_e32 v10, 0xd13e840, v10
	v_add_u32_e32 v3, s16, v2
	v_cmp_gt_u32_e64 s[14:15], s5, v3
	v_lshrrev_b32_e32 v12, 7, v3
	v_mul_hi_u32 v12, v12, s4
	v_lshrrev_b32_e32 v12, 3, v12
	v_mul_u32_u24_e32 v13, 0x580, v12
	v_sub_u32_e32 v13, v3, v13
	v_and_b32_e32 v14, 1, v12
	v_sub_u32_e32 v7, v12, v14
	v_lshl_add_u32 v7, v7, 2, v14
	v_add_u32_e32 v7, 0x2006, v7
	v_mul_u32_u24_e32 v7, 0x5800, v7
	v_lshl_add_u32 v7, v13, 4, v7
	v_mul_u32_u24_e32 v11, 0xb000, v12
	v_lshl_add_u32 v11, v13, 5, v11
	v_add_u32_e32 v11, 0xd13e840, v11
	s_and_b64 exec, s[6:7], s[8:9]
	global_load_dwordx4 v[240:243], v4, s[30:31]
	s_and_b64 exec, s[6:7], s[10:11]
	global_load_dwordx4 v[244:247], v5, s[30:31]
	s_and_b64 exec, s[6:7], s[12:13]
	global_load_dwordx4 v[248:251], v6, s[30:31]
	s_and_b64 exec, s[6:7], s[14:15]
	global_load_dwordx4 v[252:255], v7, s[30:31]
	s_waitcnt vmcnt(0)
	s_and_b64 exec, s[6:7], s[8:9]
	v_lshlrev_b32_e32 v12, 16, v240
	v_and_b32_e32 v13, 0xffff0000, v240
	v_lshlrev_b32_e32 v14, 16, v241
	v_and_b32_e32 v15, 0xffff0000, v241
	global_store_dwordx4 v8, v[12:15], s[28:29]
	v_lshlrev_b32_e32 v240, 16, v242
	v_and_b32_e32 v241, 0xffff0000, v242
	v_lshlrev_b32_e32 v242, 16, v243
	v_and_b32_e32 v243, 0xffff0000, v243
	global_store_dwordx4 v8, v[240:243], s[28:29] offset:16
	s_nop 1
	s_and_b64 exec, s[6:7], s[10:11]
	v_lshlrev_b32_e32 v12, 16, v244
	v_and_b32_e32 v13, 0xffff0000, v244
	v_lshlrev_b32_e32 v14, 16, v245
	v_and_b32_e32 v15, 0xffff0000, v245
	global_store_dwordx4 v9, v[12:15], s[28:29]
	v_lshlrev_b32_e32 v244, 16, v246
	v_and_b32_e32 v245, 0xffff0000, v246
	v_lshlrev_b32_e32 v246, 16, v247
	v_and_b32_e32 v247, 0xffff0000, v247
	global_store_dwordx4 v9, v[244:247], s[28:29] offset:16
	s_nop 1
	s_and_b64 exec, s[6:7], s[12:13]
	v_lshlrev_b32_e32 v12, 16, v248
	v_and_b32_e32 v13, 0xffff0000, v248
	v_lshlrev_b32_e32 v14, 16, v249
	v_and_b32_e32 v15, 0xffff0000, v249
	global_store_dwordx4 v10, v[12:15], s[28:29]
	v_lshlrev_b32_e32 v248, 16, v250
	v_and_b32_e32 v249, 0xffff0000, v250
	v_lshlrev_b32_e32 v250, 16, v251
	v_and_b32_e32 v251, 0xffff0000, v251
	global_store_dwordx4 v10, v[248:251], s[28:29] offset:16
	s_nop 1
	s_and_b64 exec, s[6:7], s[14:15]
	v_lshlrev_b32_e32 v12, 16, v252
	v_and_b32_e32 v13, 0xffff0000, v252
	v_lshlrev_b32_e32 v14, 16, v253
	v_and_b32_e32 v15, 0xffff0000, v253
	global_store_dwordx4 v11, v[12:15], s[28:29]
	v_lshlrev_b32_e32 v252, 16, v254
	v_and_b32_e32 v253, 0xffff0000, v254
	v_lshlrev_b32_e32 v254, 16, v255
	v_and_b32_e32 v255, 0xffff0000, v255
	global_store_dwordx4 v11, v[252:255], s[28:29] offset:16
	s_nop 1
	s_mov_b64 exec, s[6:7]
	v_add_u32_e32 v0, s16, v3
	v_cmp_gt_u32_e32 vcc, s5, v0
	s_and_b64 exec, exec, vcc
	s_cbranch_execnz .Lsffn2_loop
	s_mov_b64 exec, s[18:19]
.Lt5_nocopy:
	s_mov_b32 s4, 0x2c0000
	v_cmp_gt_i32_e32 vcc, s4, v144
	s_and_saveexec_b64 s[0:1], vcc
	v_readlane_b32 s19, v239, 6
	s_cbranch_execz .LBB0_1013
	s_mov_b32 s4, 0xba2e8ba3
	s_mov_b32 s5, 0x58000
	v_mov_b32_e32 v0, v144
.Lsffn_loop:
	s_mov_b64 s[6:7], exec
	v_cmp_gt_u32_e64 s[8:9], s5, v0
	v_lshrrev_b32_e32 v12, 7, v0
	v_mul_hi_u32 v12, v12, s4
	v_lshrrev_b32_e32 v12, 3, v12
	v_mul_u32_u24_e32 v13, 0x580, v12
	v_sub_u32_e32 v13, v0, v13
	v_and_b32_e32 v14, 1, v12
	v_sub_u32_e32 v4, v12, v14
	v_lshl_add_u32 v4, v4, 2, v14
	v_add_u32_e32 v4, 0x2006, v4
	v_mul_u32_u24_e32 v4, 0x5800, v4
	v_lshl_add_u32 v4, v13, 4, v4
	v_mul_u32_u24_e32 v8, 0xb000, v12
	v_lshl_add_u32 v8, v13, 5, v8
	v_add_u32_e32 v8, 0xd13e840, v8
	v_cmp_gt_u32_e32 vcc, 0x400, v13
	s_and_b64 s[8:9], s[8:9], vcc
	v_add_u32_e32 v1, s22, v0
	v_cmp_gt_u32_e64 s[10:11], s5, v1
	v_lshrrev_b32_e32 v12, 7, v1
	v_mul_hi_u32 v12, v12, s4
	v_lshrrev_b32_e32 v12, 3, v12
	v_mul_u32_u24_e32 v13, 0x580, v12
	v_sub_u32_e32 v13, v1, v13
	v_and_b32_e32 v14, 1, v12
	v_sub_u32_e32 v5, v12, v14
	v_lshl_add_u32 v5, v5, 2, v14
	v_add_u32_e32 v5, 0x2006, v5
	v_mul_u32_u24_e32 v5, 0x5800, v5
	v_lshl_add_u32 v5, v13, 4, v5
	v_mul_u32_u24_e32 v9, 0xb000, v12
	v_lshl_add_u32 v9, v13, 5, v9
	v_add_u32_e32 v9, 0xd13e840, v9
	v_cmp_gt_u32_e32 vcc, 0x400, v13
	s_and_b64 s[10:11], s[10:11], vcc
	v_add_u32_e32 v2, s22, v1
	v_cmp_gt_u32_e64 s[12:13], s5, v2
	v_lshrrev_b32_e32 v12, 7, v2
	v_mul_hi_u32 v12, v12, s4
	v_lshrrev_b32_e32 v12, 3, v12
	v_mul_u32_u24_e32 v13, 0x580, v12
	v_sub_u32_e32 v13, v2, v13
	v_and_b32_e32 v14, 1, v12
	v_sub_u32_e32 v6, v12, v14
	v_lshl_add_u32 v6, v6, 2, v14
	v_add_u32_e32 v6, 0x2006, v6
	v_mul_u32_u24_e32 v6, 0x5800, v6
	v_lshl_add_u32 v6, v13, 4, v6
	v_mul_u32_u24_e32 v10, 0xb000, v12
	v_lshl_add_u32 v10, v13, 5, v10
	v_add_u32_e32 v10, 0xd13e840, v10
	v_cmp_gt_u32_e32 vcc, 0x400, v13
	s_and_b64 s[12:13], s[12:13], vcc
	v_add_u32_e32 v3, s22, v2
	v_cmp_gt_u32_e64 s[14:15], s5, v3
	v_lshrrev_b32_e32 v12, 7, v3
	v_mul_hi_u32 v12, v12, s4
	v_lshrrev_b32_e32 v12, 3, v12
	v_mul_u32_u24_e32 v13, 0x580, v12
	v_sub_u32_e32 v13, v3, v13
	v_and_b32_e32 v14, 1, v12
	v_sub_u32_e32 v7, v12, v14
	v_lshl_add_u32 v7, v7, 2, v14
	v_add_u32_e32 v7, 0x2006, v7
	v_mul_u32_u24_e32 v7, 0x5800, v7
	v_lshl_add_u32 v7, v13, 4, v7
	v_mul_u32_u24_e32 v11, 0xb000, v12
	v_lshl_add_u32 v11, v13, 5, v11
	v_add_u32_e32 v11, 0xd13e840, v11
	v_cmp_gt_u32_e32 vcc, 0x400, v13
	s_and_b64 s[14:15], s[14:15], vcc
	s_and_b64 exec, s[6:7], s[8:9]
	global_load_dwordx4 v[240:243], v4, s[30:31]
	s_and_b64 exec, s[6:7], s[10:11]
	global_load_dwordx4 v[244:247], v5, s[30:31]
	s_and_b64 exec, s[6:7], s[12:13]
	global_load_dwordx4 v[248:251], v6, s[30:31]
	s_and_b64 exec, s[6:7], s[14:15]
	global_load_dwordx4 v[252:255], v7, s[30:31]
	s_waitcnt vmcnt(0)
	s_and_b64 exec, s[6:7], s[8:9]
	v_lshlrev_b32_e32 v12, 16, v240
	v_and_b32_e32 v13, 0xffff0000, v240
	v_lshlrev_b32_e32 v14, 16, v241
	v_and_b32_e32 v15, 0xffff0000, v241
	global_store_dwordx4 v8, v[12:15], s[28:29]
	v_lshlrev_b32_e32 v240, 16, v242
	v_and_b32_e32 v241, 0xffff0000, v242
	v_lshlrev_b32_e32 v242, 16, v243
	v_and_b32_e32 v243, 0xffff0000, v243
	global_store_dwordx4 v8, v[240:243], s[28:29] offset:16
	s_nop 1
	s_and_b64 exec, s[6:7], s[10:11]
	v_lshlrev_b32_e32 v12, 16, v244
	v_and_b32_e32 v13, 0xffff0000, v244
	v_lshlrev_b32_e32 v14, 16, v245
	v_and_b32_e32 v15, 0xffff0000, v245
	global_store_dwordx4 v9, v[12:15], s[28:29]
	v_lshlrev_b32_e32 v244, 16, v246
	v_and_b32_e32 v245, 0xffff0000, v246
	v_lshlrev_b32_e32 v246, 16, v247
	v_and_b32_e32 v247, 0xffff0000, v247
	global_store_dwordx4 v9, v[244:247], s[28:29] offset:16
	s_nop 1
	s_and_b64 exec, s[6:7], s[12:13]
	v_lshlrev_b32_e32 v12, 16, v248
	v_and_b32_e32 v13, 0xffff0000, v248
	v_lshlrev_b32_e32 v14, 16, v249
	v_and_b32_e32 v15, 0xffff0000, v249
	global_store_dwordx4 v10, v[12:15], s[28:29]
	v_lshlrev_b32_e32 v248, 16, v250
	v_and_b32_e32 v249, 0xffff0000, v250
	v_lshlrev_b32_e32 v250, 16, v251
	v_and_b32_e32 v251, 0xffff0000, v251
	global_store_dwordx4 v10, v[248:251], s[28:29] offset:16
	s_nop 1
	s_and_b64 exec, s[6:7], s[14:15]
	v_lshlrev_b32_e32 v12, 16, v252
	v_and_b32_e32 v13, 0xffff0000, v252
	v_lshlrev_b32_e32 v14, 16, v253
	v_and_b32_e32 v15, 0xffff0000, v253
	global_store_dwordx4 v11, v[12:15], s[28:29]
	v_lshlrev_b32_e32 v252, 16, v254
	v_and_b32_e32 v253, 0xffff0000, v254
	v_lshlrev_b32_e32 v254, 16, v255
	v_and_b32_e32 v255, 0xffff0000, v255
	global_store_dwordx4 v11, v[252:255], s[28:29] offset:16
	s_nop 1
	s_mov_b64 exec, s[6:7]
	v_add_u32_e32 v0, s22, v3
	v_cmp_gt_u32_e32 vcc, s5, v0
	s_and_b64 exec, exec, vcc
	s_cbranch_execnz .Lsffn_loop
